# D2 residual stream: nt hint on the f32 x loads and out stores (touched once per layer)
# speedup vs baseline: 1.0587x; 1.0153x over previous
; DI float lo16(unsigned w) { return __uint_as_float(w << 16); }
; DI float hi16(unsigned w) { return __uint_as_float(w & 0xffff0000u); }
; template <int NR>
; DI void resid_rows(const Params& p, int l, int row0, const float* xin) {
;     ...
;   u32x2 ob[NR][4]; f32x4 xv[NR][4]; f32x4 sq[NR][2];
; #pragma unroll
;   for (int r = 0; r < NR; ++r) {
;     const size_t row = (size_t)(row0 + r);
;     sq[r][0] = *(const f32x4*)(ssq + row * 16); sq[r][1] = *(const f32x4*)(ssq + row * 16 + 4);
; #pragma unroll
;     for (int i = 0; i < 4; ++i) { const int idx = i * 256 + lane * 4; ob[r][i] = *(const u32x2*)(outb + row * 1024 + idx); xv[r][i] = *(const f32x4*)(xin + row * 1024 + idx); }
;   }
;   f32x4 gq[4];
; #pragma unroll
;   for (int i = 0; i < 4; ++i) gq[i] = *(const f32x4*)(p.g_post + l * 1024 + i * 256 + lane * 4);
;   u16* xb = (u16*)(ws_ + OFF_XB);
; #pragma unroll
;   for (int r = 0; r < NR; ++r) {
;     const size_t row = (size_t)(row0 + r);
;     const float ss = ((sq[r][0][0] + sq[r][0][1]) + (sq[r][0][2] + sq[r][0][3])) + ((sq[r][1][0] + sq[r][1][1]) + (sq[r][1][2] + sq[r][1][3]));
;     const float r2 = rsqrtf(ss * (1.f / 1024.f) + 1e-6f);
;     float s2 = 0.f;
; #pragma unroll
;     for (int i = 0; i < 4; ++i) {
;       const int idx = i * 256 + lane * 4;
;       const f32x4 o = {lo16(ob[r][i][0]), hi16(ob[r][i][0]), lo16(ob[r][i][1]), hi16(ob[r][i][1])};
;       f32x4 xn;
; #pragma unroll
;       for (int e = 0; e < 4; ++e) { xn[e] = xv[r][i][e] + o[e] * r2 * gq[i][e]; s2 += xn[e] * xn[e]; }
;       *(f32x4*)(p.out + row * 1024 + idx) = xn;
.LBB0_592:
	s_mov_b64 s[6:7], 0
	s_add_u32 s8, s90, s6
	s_addc_u32 s9, s91, s7
	s_add_u32 s6, s8, 0xd4f0000
	v_mov_b32_e32 v0, v176
	s_addc_u32 s7, s9, 0
	s_add_u32 s10, s8, 0xb250000
	v_ashrrev_i32_e32 v105, 31, v104
	v_and_b32_e32 v149, 63, v0
	s_addc_u32 s11, s9, 0
	s_waitcnt lgkmcnt(0)
	v_lshlrev_b64 v[0:1], 6, v[104:105]
	v_lshl_add_u64 v[0:1], s[10:11], 0, v[0:1]
	v_lshlrev_b64 v[146:147], 11, v[104:105]
	v_lshlrev_b64 v[154:155], 12, v[104:105]
	global_load_dwordx4 v[100:103], v[0:1], off
	global_load_dwordx4 v[142:145], v[0:1], off offset:16
	v_lshl_add_u64 v[0:1], s[6:7], 0, v[146:147]
	v_lshl_add_u64 v[2:3], s[0:1], 0, v[154:155]
	v_lshlrev_b32_e32 v178, 3, v149
	v_lshlrev_b32_e32 v156, 4, v149
	v_mov_b32_e32 v157, v179
	v_add_u32_e32 v124, 1, v104
	v_lshl_add_u64 v[0:1], v[0:1], 0, v[178:179]
	v_lshl_add_u64 v[2:3], v[2:3], 0, v[156:157]
	v_ashrrev_i32_e32 v125, 31, v124
	global_load_dwordx4 v[150:153], v[2:3], off nt
	global_load_dwordx4 v[96:99], v[2:3], off offset:1024 nt
	global_load_dwordx2 v[158:159], v[0:1], off
	global_load_dwordx2 v[140:141], v[0:1], off offset:512
	global_load_dwordx2 v[138:139], v[0:1], off offset:1024
	global_load_dwordx2 v[136:137], v[0:1], off offset:1536
	global_load_dwordx4 v[92:95], v[2:3], off offset:2048 nt
	global_load_dwordx4 v[88:91], v[2:3], off offset:3072 nt
	v_lshlrev_b64 v[0:1], 6, v[124:125]
	v_lshl_add_u64 v[0:1], s[10:11], 0, v[0:1]
	global_load_dwordx4 v[80:83], v[0:1], off offset:16
	global_load_dwordx4 v[84:87], v[0:1], off
	v_lshlrev_b64 v[0:1], 11, v[124:125]
	v_lshlrev_b64 v[2:3], 12, v[124:125]
	v_lshl_add_u64 v[0:1], s[6:7], 0, v[0:1]
	v_lshl_add_u64 v[2:3], s[0:1], 0, v[2:3]
	v_add_u32_e32 v114, 2, v104
	v_lshl_add_u64 v[0:1], v[0:1], 0, v[178:179]
	v_lshl_add_u64 v[2:3], v[2:3], 0, v[156:157]
	v_ashrrev_i32_e32 v115, 31, v114
	global_load_dwordx4 v[76:79], v[2:3], off nt
	global_load_dwordx4 v[72:75], v[2:3], off offset:1024 nt
	global_load_dwordx2 v[134:135], v[0:1], off
	global_load_dwordx2 v[132:133], v[0:1], off offset:512
	global_load_dwordx2 v[130:131], v[0:1], off offset:1024
	global_load_dwordx2 v[128:129], v[0:1], off offset:1536
	global_load_dwordx4 v[68:71], v[2:3], off offset:2048 nt
	global_load_dwordx4 v[64:67], v[2:3], off offset:3072 nt
	v_lshlrev_b64 v[0:1], 6, v[114:115]
	v_lshl_add_u64 v[0:1], s[10:11], 0, v[0:1]
	v_lshlrev_b64 v[2:3], 12, v[114:115]
	global_load_dwordx4 v[56:59], v[0:1], off offset:16
	global_load_dwordx4 v[60:63], v[0:1], off
	v_lshlrev_b64 v[0:1], 11, v[114:115]
	v_lshl_add_u64 v[2:3], s[0:1], 0, v[2:3]
	v_lshl_add_u64 v[0:1], s[6:7], 0, v[0:1]
	v_lshl_add_u64 v[2:3], v[2:3], 0, v[156:157]
	v_lshl_add_u64 v[0:1], v[0:1], 0, v[178:179]
	global_load_dwordx4 v[52:55], v[2:3], off nt
	global_load_dwordx4 v[48:51], v[2:3], off offset:1024 nt
	global_load_dwordx2 v[126:127], v[0:1], off
	global_load_dwordx2 v[122:123], v[0:1], off offset:512
	global_load_dwordx2 v[120:121], v[0:1], off offset:1024
	global_load_dwordx2 v[118:119], v[0:1], off offset:1536
	global_load_dwordx4 v[44:47], v[2:3], off offset:2048 nt
	global_load_dwordx4 v[40:43], v[2:3], off offset:3072 nt
	v_add_u32_e32 v106, 3, v104
	v_ashrrev_i32_e32 v107, 31, v106
	v_lshlrev_b64 v[0:1], 6, v[106:107]
	v_lshl_add_u64 v[0:1], s[10:11], 0, v[0:1]
	global_load_dwordx4 v[32:35], v[0:1], off offset:16
	global_load_dwordx4 v[36:39], v[0:1], off
	v_lshlrev_b64 v[0:1], 11, v[106:107]
	v_lshlrev_b64 v[2:3], 12, v[106:107]
	v_lshl_add_u64 v[0:1], s[6:7], 0, v[0:1]
	v_lshl_add_u64 v[2:3], s[0:1], 0, v[2:3]
	v_lshl_add_u64 v[0:1], v[0:1], 0, v[178:179]
	v_lshl_add_u64 v[2:3], v[2:3], 0, v[156:157]
	global_load_dwordx4 v[24:27], v156, s[2:3]
	global_load_dwordx4 v[28:31], v[2:3], off nt
	global_load_dwordx4 v[16:19], v[2:3], off offset:1024 nt
	global_load_dwordx2 v[116:117], v[0:1], off
	global_load_dwordx2 v[112:113], v[0:1], off offset:512
	global_load_dwordx2 v[110:111], v[0:1], off offset:1024
	global_load_dwordx2 v[108:109], v[0:1], off offset:1536
	global_load_dwordx4 v[8:11], v[2:3], off offset:2048 nt
	s_nop 0
	global_load_dwordx4 v[0:3], v[2:3], off offset:3072 nt
	s_nop 0
	global_load_dwordx4 v[20:23], v156, s[2:3] offset:1024
	global_load_dwordx4 v[12:15], v156, s[2:3] offset:2048
	global_load_dwordx4 v[4:7], v156, s[2:3] offset:3072
	s_add_u32 s6, s8, 0x2a40000
	s_addc_u32 s7, s9, 0
	v_lshlrev_b32_e32 v148, 2, v149
	s_waitcnt vmcnt(43)
	v_mov_b32_e32 v160, v100
	s_waitcnt vmcnt(42)
	v_mov_b32_e32 v161, v142
	v_mov_b32_e32 v142, v101
	v_pk_add_f32 v[100:101], v[160:161], v[142:143]
	v_mov_b32_e32 v142, v102
	v_mov_b32_e32 v143, v144
	v_mov_b32_e32 v144, v103
	v_pk_add_f32 v[102:103], v[142:143], v[144:145]
	v_lshl_add_u64 v[142:143], s[6:7], 0, v[146:147]
	v_pk_add_f32 v[100:101], v[100:101], v[102:103]
	s_waitcnt vmcnt(39)
	v_lshlrev_b32_e32 v102, 16, v159
	v_add_f32_e32 v100, v100, v101
	v_fmamk_f32 v100, v100, 0x3a800000, v192
	v_mul_f32_e32 v101, 0x4b800000, v100
	v_cmp_gt_f32_e32 vcc, s92, v100
	v_and_b32_e32 v103, 0xffff0000, v159
	v_lshl_add_u64 v[146:147], s[88:89], 0, v[154:155]
	v_cndmask_b32_e32 v100, v100, v101, vcc
	v_rsq_f32_e32 v100, v100
	v_lshl_add_u64 v[146:147], v[146:147], 0, v[156:157]
	v_mul_f32_e32 v101, 0x45800000, v100
	v_cndmask_b32_e32 v144, v100, v101, vcc
	v_lshlrev_b32_e32 v100, 16, v158
	v_and_b32_e32 v101, 0xffff0000, v158
	v_pk_mul_f32 v[100:101], v[144:145], v[100:101] op_sel_hi:[0,1]
	v_pk_mul_f32 v[102:103], v[144:145], v[102:103] op_sel_hi:[0,1]
	v_cndmask_b32_e64 v145, 0, 1, s[4:5]
	v_cmp_ne_u32_e64 s[36:37], 1, v145
	s_andn2_b64 vcc, exec, s[4:5]
	s_waitcnt vmcnt(11)
	v_pk_fma_f32 v[100:101], v[100:101], v[24:25], v[150:151]
	v_pk_fma_f32 v[102:103], v[102:103], v[26:27], v[152:153]
	global_store_dwordx4 v[146:147], v[100:103], off nt
	s_cbranch_vccnz .LBB0_594
	v_lshlrev_b32_e32 v178, 1, v148
	v_cvt_pk_bf16_f32 v150, v100, v101
	v_cvt_pk_bf16_f32 v151, v102, v103
	v_lshl_add_u64 v[152:153], v[142:143], 0, v[178:179]
	global_store_dwordx2 v[152:153], v[150:151], off
; DI float lo16(unsigned w) { return __uint_as_float(w << 16); }
; DI float hi16(unsigned w) { return __uint_as_float(w & 0xffff0000u); }
; template <int NR>
; DI void resid_rows(const Params& p, int l, int row0, const float* xin) {
;     ...
;     for (int i = 0; i < 4; ++i) {
;       const int idx = i * 256 + lane * 4;
;       const f32x4 o = {lo16(ob[r][i][0]), hi16(ob[r][i][0]), lo16(ob[r][i][1]), hi16(ob[r][i][1])};
;       f32x4 xn;
; #pragma unroll
;       for (int e = 0; e < 4; ++e) { xn[e] = xv[r][i][e] + o[e] * r2 * gq[i][e]; s2 += xn[e] * xn[e]; }
;       *(f32x4*)(p.out + row * 1024 + idx) = xn;
;       if (l < 3) { u32x2 o2; o2[0] = pk2(xn[0], xn[1]); o2[1] = pk2(xn[2], xn[3]); *(u32x2*)(xb + row * 1024 + idx) = o2; }
.LBB0_594:
	v_mov_b32_e32 v145, v144
	v_lshlrev_b32_e32 v150, 16, v140
	v_and_b32_e32 v151, 0xffff0000, v140
	v_lshlrev_b32_e32 v140, 16, v141
	v_and_b32_e32 v141, 0xffff0000, v141
	v_pk_mul_f32 v[150:151], v[144:145], v[150:151]
	v_pk_mul_f32 v[140:141], v[144:145], v[140:141]
	s_waitcnt vmcnt(3)
	v_pk_fma_f32 v[96:97], v[150:151], v[20:21], v[96:97]
	v_pk_fma_f32 v[98:99], v[140:141], v[22:23], v[98:99]
	s_and_b64 vcc, exec, s[36:37]
	global_store_dwordx4 v[146:147], v[96:99], off offset:1024 nt
	s_cbranch_vccnz .LBB0_596
	v_lshlrev_b32_e32 v178, 1, v148
	v_cvt_pk_bf16_f32 v140, v96, v97
	v_cvt_pk_bf16_f32 v141, v98, v99
	v_lshl_add_u64 v[150:151], v[142:143], 0, v[178:179]
	global_store_dwordx2 v[150:151], v[140:141], off offset:512
.LBB0_596:
	v_lshlrev_b32_e32 v140, 16, v138
	v_and_b32_e32 v141, 0xffff0000, v138
	v_lshlrev_b32_e32 v138, 16, v139
	v_and_b32_e32 v139, 0xffff0000, v139
	v_pk_mul_f32 v[140:141], v[144:145], v[140:141]
	v_pk_mul_f32 v[138:139], v[144:145], v[138:139]
	s_waitcnt vmcnt(3)
	v_pk_fma_f32 v[92:93], v[140:141], v[12:13], v[92:93]
	v_pk_fma_f32 v[94:95], v[138:139], v[14:15], v[94:95]
	s_and_b64 vcc, exec, s[36:37]
	global_store_dwordx4 v[146:147], v[92:95], off offset:2048 nt
	s_cbranch_vccnz .LBB0_598
	v_lshlrev_b32_e32 v178, 1, v148
	v_cvt_pk_bf16_f32 v138, v92, v93
	v_cvt_pk_bf16_f32 v139, v94, v95
	v_lshl_add_u64 v[140:141], v[142:143], 0, v[178:179]
	global_store_dwordx2 v[140:141], v[138:139], off offset:1024
.LBB0_598:
	v_lshlrev_b32_e32 v138, 16, v136
	v_and_b32_e32 v139, 0xffff0000, v136
	v_lshlrev_b32_e32 v136, 16, v137
	v_and_b32_e32 v137, 0xffff0000, v137
	v_pk_mul_f32 v[138:139], v[144:145], v[138:139]
	v_pk_mul_f32 v[136:137], v[144:145], v[136:137]
	s_waitcnt vmcnt(3)
	v_pk_fma_f32 v[88:89], v[138:139], v[4:5], v[88:89]
	v_pk_fma_f32 v[90:91], v[136:137], v[6:7], v[90:91]
	s_and_b64 vcc, exec, s[36:37]
	global_store_dwordx4 v[146:147], v[88:91], off offset:3072 nt
	s_cbranch_vccnz .LBB0_600
	v_lshlrev_b32_e32 v178, 1, v148
	v_cvt_pk_bf16_f32 v136, v88, v89
	v_cvt_pk_bf16_f32 v137, v90, v91
	v_lshl_add_u64 v[138:139], v[142:143], 0, v[178:179]
	global_store_dwordx2 v[138:139], v[136:137], off offset:1536

; DI float lo16(unsigned w) { return __uint_as_float(w << 16); }
; DI float hi16(unsigned w) { return __uint_as_float(w & 0xffff0000u); }
; template <int NR>
; DI void resid_rows(const Params& p, int l, int row0, const float* xin) {
;     ...
;   for (int r = 0; r < NR; ++r) {
;     const size_t row = (size_t)(row0 + r);
;     const float ss = ((sq[r][0][0] + sq[r][0][1]) + (sq[r][0][2] + sq[r][0][3])) + ((sq[r][1][0] + sq[r][1][1]) + (sq[r][1][2] + sq[r][1][3]));
;     const float r2 = rsqrtf(ss * (1.f / 1024.f) + 1e-6f);
;     float s2 = 0.f;
; #pragma unroll
;     for (int i = 0; i < 4; ++i) {
;       const int idx = i * 256 + lane * 4;
;       const f32x4 o = {lo16(ob[r][i][0]), hi16(ob[r][i][0]), lo16(ob[r][i][1]), hi16(ob[r][i][1])};
;       f32x4 xn;
; #pragma unroll
;       for (int e = 0; e < 4; ++e) { xn[e] = xv[r][i][e] + o[e] * r2 * gq[i][e]; s2 += xn[e] * xn[e]; }
;       *(f32x4*)(p.out + row * 1024 + idx) = xn;
;       if (l < 3) { u32x2 o2; o2[0] = pk2(xn[0], xn[1]); o2[1] = pk2(xn[2], xn[3]); *(u32x2*)(xb + row * 1024 + idx) = o2; }
.LBB0_602:
	s_or_b64 exec, exec, s[10:11]
	v_mov_b32_e32 v94, v84
	s_waitcnt lgkmcnt(0)
	v_mov_b32_e32 v95, v80
	v_mov_b32_e32 v80, v85
	v_mov_b32_e32 v84, v86
	v_mov_b32_e32 v85, v82
	v_mov_b32_e32 v82, v87
	v_pk_add_f32 v[80:81], v[94:95], v[80:81]
	v_pk_add_f32 v[82:83], v[84:85], v[82:83]
	v_lshlrev_b32_e32 v86, 16, v134
	v_pk_add_f32 v[80:81], v[80:81], v[82:83]
	v_and_b32_e32 v87, 0xffff0000, v134
	v_add_f32_e32 v80, v80, v81
	v_fmamk_f32 v80, v80, 0x3a800000, v192
	v_mul_f32_e32 v81, 0x4b800000, v80
	v_cmp_gt_f32_e32 vcc, s92, v80
	v_lshlrev_b64 v[84:85], 10, v[124:125]
	v_lshlrev_b32_e32 v178, 2, v148
	v_cndmask_b32_e32 v80, v80, v81, vcc
	v_rsq_f32_e32 v80, v80
	s_nop 0
	v_mul_f32_e32 v81, 0x45800000, v80
	v_cndmask_b32_e32 v82, v80, v81, vcc
	v_pk_mul_f32 v[86:87], v[82:83], v[86:87] op_sel_hi:[0,1]
	v_pk_fma_f32 v[76:77], v[86:87], v[24:25], v[76:77]
	v_lshlrev_b32_e32 v86, 16, v135
	v_and_b32_e32 v87, 0xffff0000, v135
	v_lshl_add_u64 v[80:81], v[84:85], 1, s[6:7]
	v_pk_mul_f32 v[86:87], v[82:83], v[86:87] op_sel_hi:[0,1]
	v_lshl_add_u64 v[84:85], v[84:85], 2, s[88:89]
	v_pk_fma_f32 v[78:79], v[86:87], v[26:27], v[78:79]
	v_lshl_add_u64 v[84:85], v[84:85], 0, v[178:179]
	s_and_b64 vcc, exec, s[36:37]
	global_store_dwordx4 v[84:85], v[76:79], off nt
	s_cbranch_vccnz .LBB0_604
	v_lshlrev_b32_e32 v94, 1, v148
	v_mov_b32_e32 v95, v179
	v_cvt_pk_bf16_f32 v86, v76, v77
	v_cvt_pk_bf16_f32 v87, v78, v79
	v_lshl_add_u64 v[94:95], v[80:81], 0, v[94:95]
	global_store_dwordx2 v[94:95], v[86:87], off
.LBB0_604:
	v_mov_b32_e32 v83, v82
	v_lshlrev_b32_e32 v86, 16, v132
	v_and_b32_e32 v87, 0xffff0000, v132
	v_pk_mul_f32 v[86:87], v[82:83], v[86:87]
	s_and_b64 vcc, exec, s[36:37]
	v_pk_fma_f32 v[72:73], v[86:87], v[20:21], v[72:73]
	v_lshlrev_b32_e32 v86, 16, v133
	v_and_b32_e32 v87, 0xffff0000, v133
	v_pk_mul_f32 v[86:87], v[82:83], v[86:87]
	s_nop 0
	v_pk_fma_f32 v[74:75], v[86:87], v[22:23], v[74:75]
	global_store_dwordx4 v[84:85], v[72:75], off offset:1024 nt
	s_cbranch_vccnz .LBB0_606
	v_lshlrev_b32_e32 v94, 1, v148
	v_mov_b32_e32 v95, v179
	v_cvt_pk_bf16_f32 v86, v72, v73
	v_cvt_pk_bf16_f32 v87, v74, v75
	v_lshl_add_u64 v[94:95], v[80:81], 0, v[94:95]
	global_store_dwordx2 v[94:95], v[86:87], off offset:512
.LBB0_606:
	v_lshlrev_b32_e32 v86, 16, v130
	v_and_b32_e32 v87, 0xffff0000, v130
	v_pk_mul_f32 v[86:87], v[82:83], v[86:87]
	s_and_b64 vcc, exec, s[36:37]
	v_pk_fma_f32 v[68:69], v[86:87], v[12:13], v[68:69]
	v_lshlrev_b32_e32 v86, 16, v131
	v_and_b32_e32 v87, 0xffff0000, v131
	v_pk_mul_f32 v[86:87], v[82:83], v[86:87]
	s_nop 0
	v_pk_fma_f32 v[70:71], v[86:87], v[14:15], v[70:71]
	global_store_dwordx4 v[84:85], v[68:71], off offset:2048 nt
	s_cbranch_vccnz .LBB0_608
	v_lshlrev_b32_e32 v94, 1, v148
	v_mov_b32_e32 v95, v179
	v_cvt_pk_bf16_f32 v86, v68, v69
	v_cvt_pk_bf16_f32 v87, v70, v71
	v_lshl_add_u64 v[94:95], v[80:81], 0, v[94:95]
	global_store_dwordx2 v[94:95], v[86:87], off offset:1024
.LBB0_608:
	v_lshlrev_b32_e32 v86, 16, v128
	v_and_b32_e32 v87, 0xffff0000, v128
	v_pk_mul_f32 v[86:87], v[82:83], v[86:87]
	s_and_b64 vcc, exec, s[36:37]
	v_pk_fma_f32 v[64:65], v[86:87], v[4:5], v[64:65]
	v_lshlrev_b32_e32 v86, 16, v129
	v_and_b32_e32 v87, 0xffff0000, v129
	v_pk_mul_f32 v[82:83], v[82:83], v[86:87]
	s_nop 0
	v_pk_fma_f32 v[66:67], v[82:83], v[6:7], v[66:67]
	global_store_dwordx4 v[84:85], v[64:67], off offset:3072 nt
	s_cbranch_vccnz .LBB0_610
	v_lshlrev_b32_e32 v84, 1, v148
	v_mov_b32_e32 v85, v179
	v_cvt_pk_bf16_f32 v82, v64, v65
	v_cvt_pk_bf16_f32 v83, v66, v67
	v_lshl_add_u64 v[80:81], v[80:81], 0, v[84:85]
	global_store_dwordx2 v[80:81], v[82:83], off offset:1536

; DI float lo16(unsigned w) { return __uint_as_float(w << 16); }
; DI float hi16(unsigned w) { return __uint_as_float(w & 0xffff0000u); }
; template <int NR>
; DI void resid_rows(const Params& p, int l, int row0, const float* xin) {
;     ...
;   for (int r = 0; r < NR; ++r) {
;     const size_t row = (size_t)(row0 + r);
;     const float ss = ((sq[r][0][0] + sq[r][0][1]) + (sq[r][0][2] + sq[r][0][3])) + ((sq[r][1][0] + sq[r][1][1]) + (sq[r][1][2] + sq[r][1][3]));
;     const float r2 = rsqrtf(ss * (1.f / 1024.f) + 1e-6f);
;     float s2 = 0.f;
; #pragma unroll
;     for (int i = 0; i < 4; ++i) {
;       const int idx = i * 256 + lane * 4;
;       const f32x4 o = {lo16(ob[r][i][0]), hi16(ob[r][i][0]), lo16(ob[r][i][1]), hi16(ob[r][i][1])};
;       f32x4 xn;
; #pragma unroll
;       for (int e = 0; e < 4; ++e) { xn[e] = xv[r][i][e] + o[e] * r2 * gq[i][e]; s2 += xn[e] * xn[e]; }
;       *(f32x4*)(p.out + row * 1024 + idx) = xn;
;       if (l < 3) { u32x2 o2; o2[0] = pk2(xn[0], xn[1]); o2[1] = pk2(xn[2], xn[3]); *(u32x2*)(xb + row * 1024 + idx) = o2; }
.LBB0_612:
	s_or_b64 exec, exec, s[10:11]
	v_mov_b32_e32 v64, v60
	s_waitcnt lgkmcnt(0)
	v_mov_b32_e32 v65, v56
	v_mov_b32_e32 v56, v61
	v_mov_b32_e32 v60, v62
	v_mov_b32_e32 v61, v58
	v_mov_b32_e32 v58, v63
	v_pk_add_f32 v[56:57], v[64:65], v[56:57]
	v_pk_add_f32 v[58:59], v[60:61], v[58:59]
	v_lshlrev_b32_e32 v62, 16, v126
	v_pk_add_f32 v[56:57], v[56:57], v[58:59]
	v_and_b32_e32 v63, 0xffff0000, v126
	v_add_f32_e32 v56, v56, v57
	v_fmamk_f32 v56, v56, 0x3a800000, v192
	v_mul_f32_e32 v57, 0x4b800000, v56
	v_cmp_gt_f32_e32 vcc, s92, v56
	v_lshlrev_b64 v[60:61], 10, v[114:115]
	s_nop 0
	v_cndmask_b32_e32 v56, v56, v57, vcc
	v_rsq_f32_e32 v56, v56
	s_nop 0
	v_mul_f32_e32 v57, 0x45800000, v56
	v_cndmask_b32_e32 v58, v56, v57, vcc
	v_pk_mul_f32 v[62:63], v[58:59], v[62:63] op_sel_hi:[0,1]
	v_pk_fma_f32 v[52:53], v[62:63], v[24:25], v[52:53]
	v_lshlrev_b32_e32 v62, 16, v127
	v_and_b32_e32 v63, 0xffff0000, v127
	v_lshl_add_u64 v[56:57], v[60:61], 1, s[6:7]
	v_pk_mul_f32 v[62:63], v[58:59], v[62:63] op_sel_hi:[0,1]
	v_lshl_add_u64 v[60:61], v[60:61], 2, s[88:89]
	v_pk_fma_f32 v[54:55], v[62:63], v[26:27], v[54:55]
	v_lshl_add_u64 v[60:61], v[60:61], 0, v[178:179]
	s_and_b64 vcc, exec, s[36:37]
	global_store_dwordx4 v[60:61], v[52:55], off nt
	s_cbranch_vccnz .LBB0_614
	v_lshlrev_b32_e32 v64, 1, v148
	v_mov_b32_e32 v65, v179
	v_cvt_pk_bf16_f32 v62, v52, v53
	v_cvt_pk_bf16_f32 v63, v54, v55
	v_lshl_add_u64 v[64:65], v[56:57], 0, v[64:65]
	global_store_dwordx2 v[64:65], v[62:63], off
.LBB0_614:
	v_mov_b32_e32 v59, v58
	v_lshlrev_b32_e32 v62, 16, v122
	v_and_b32_e32 v63, 0xffff0000, v122
	v_pk_mul_f32 v[62:63], v[58:59], v[62:63]
	s_and_b64 vcc, exec, s[36:37]
	v_pk_fma_f32 v[48:49], v[62:63], v[20:21], v[48:49]
	v_lshlrev_b32_e32 v62, 16, v123
	v_and_b32_e32 v63, 0xffff0000, v123
	v_pk_mul_f32 v[62:63], v[58:59], v[62:63]
	s_nop 0
	v_pk_fma_f32 v[50:51], v[62:63], v[22:23], v[50:51]
	global_store_dwordx4 v[60:61], v[48:51], off offset:1024 nt
	s_cbranch_vccnz .LBB0_616
	v_lshlrev_b32_e32 v64, 1, v148
	v_mov_b32_e32 v65, v179
	v_cvt_pk_bf16_f32 v62, v48, v49
	v_cvt_pk_bf16_f32 v63, v50, v51
	v_lshl_add_u64 v[64:65], v[56:57], 0, v[64:65]
	global_store_dwordx2 v[64:65], v[62:63], off offset:512
.LBB0_616:
	v_lshlrev_b32_e32 v62, 16, v120
	v_and_b32_e32 v63, 0xffff0000, v120
	v_pk_mul_f32 v[62:63], v[58:59], v[62:63]
	s_and_b64 vcc, exec, s[36:37]
	v_pk_fma_f32 v[44:45], v[62:63], v[12:13], v[44:45]
	v_lshlrev_b32_e32 v62, 16, v121
	v_and_b32_e32 v63, 0xffff0000, v121
	v_pk_mul_f32 v[62:63], v[58:59], v[62:63]
	s_nop 0
	v_pk_fma_f32 v[46:47], v[62:63], v[14:15], v[46:47]
	global_store_dwordx4 v[60:61], v[44:47], off offset:2048 nt
	s_cbranch_vccnz .LBB0_618
	v_lshlrev_b32_e32 v64, 1, v148
	v_mov_b32_e32 v65, v179
	v_cvt_pk_bf16_f32 v62, v44, v45
	v_cvt_pk_bf16_f32 v63, v46, v47
	v_lshl_add_u64 v[64:65], v[56:57], 0, v[64:65]
	global_store_dwordx2 v[64:65], v[62:63], off offset:1024
.LBB0_618:
	v_lshlrev_b32_e32 v62, 16, v118
	v_and_b32_e32 v63, 0xffff0000, v118
	v_pk_mul_f32 v[62:63], v[58:59], v[62:63]
	s_and_b64 vcc, exec, s[36:37]
	v_pk_fma_f32 v[40:41], v[62:63], v[4:5], v[40:41]
	v_lshlrev_b32_e32 v62, 16, v119
	v_and_b32_e32 v63, 0xffff0000, v119
	v_pk_mul_f32 v[58:59], v[58:59], v[62:63]
	s_nop 0
	v_pk_fma_f32 v[42:43], v[58:59], v[6:7], v[42:43]
	global_store_dwordx4 v[60:61], v[40:43], off offset:3072 nt
	s_cbranch_vccnz .LBB0_620
	v_lshlrev_b32_e32 v60, 1, v148
	v_mov_b32_e32 v61, v179
	v_cvt_pk_bf16_f32 v58, v40, v41
	v_cvt_pk_bf16_f32 v59, v42, v43
	v_lshl_add_u64 v[56:57], v[56:57], 0, v[60:61]
	global_store_dwordx2 v[56:57], v[58:59], off offset:1536

; DI float lo16(unsigned w) { return __uint_as_float(w << 16); }
; DI float hi16(unsigned w) { return __uint_as_float(w & 0xffff0000u); }
; template <int NR>
; DI void resid_rows(const Params& p, int l, int row0, const float* xin) {
;     ...
;   for (int r = 0; r < NR; ++r) {
;     const size_t row = (size_t)(row0 + r);
;     const float ss = ((sq[r][0][0] + sq[r][0][1]) + (sq[r][0][2] + sq[r][0][3])) + ((sq[r][1][0] + sq[r][1][1]) + (sq[r][1][2] + sq[r][1][3]));
;     const float r2 = rsqrtf(ss * (1.f / 1024.f) + 1e-6f);
;     float s2 = 0.f;
; #pragma unroll
;     for (int i = 0; i < 4; ++i) {
;       const int idx = i * 256 + lane * 4;
;       const f32x4 o = {lo16(ob[r][i][0]), hi16(ob[r][i][0]), lo16(ob[r][i][1]), hi16(ob[r][i][1])};
;       f32x4 xn;
; #pragma unroll
;       for (int e = 0; e < 4; ++e) { xn[e] = xv[r][i][e] + o[e] * r2 * gq[i][e]; s2 += xn[e] * xn[e]; }
;       *(f32x4*)(p.out + row * 1024 + idx) = xn;
;       if (l < 3) { u32x2 o2; o2[0] = pk2(xn[0], xn[1]); o2[1] = pk2(xn[2], xn[3]); *(u32x2*)(xb + row * 1024 + idx) = o2; }
.LBB0_622:
	s_or_b64 exec, exec, s[10:11]
	v_mov_b32_e32 v40, v36
	s_waitcnt lgkmcnt(0)
	v_mov_b32_e32 v41, v32
	v_mov_b32_e32 v32, v37
	v_mov_b32_e32 v36, v38
	v_mov_b32_e32 v37, v34
	v_mov_b32_e32 v34, v39
	v_pk_add_f32 v[32:33], v[40:41], v[32:33]
	v_pk_add_f32 v[34:35], v[36:37], v[34:35]
	v_lshlrev_b32_e32 v38, 16, v116
	v_pk_add_f32 v[32:33], v[32:33], v[34:35]
	v_and_b32_e32 v39, 0xffff0000, v116
	v_add_f32_e32 v32, v32, v33
	v_fmamk_f32 v32, v32, 0x3a800000, v192
	v_mul_f32_e32 v33, 0x4b800000, v32
	v_cmp_gt_f32_e32 vcc, s92, v32
	v_lshlrev_b64 v[36:37], 10, v[106:107]
	s_nop 0
	v_cndmask_b32_e32 v32, v32, v33, vcc
	v_rsq_f32_e32 v32, v32
	s_nop 0
	v_mul_f32_e32 v33, 0x45800000, v32
	v_cndmask_b32_e32 v34, v32, v33, vcc
	v_pk_mul_f32 v[38:39], v[34:35], v[38:39] op_sel_hi:[0,1]
	v_pk_fma_f32 v[24:25], v[24:25], v[38:39], v[28:29]
	v_lshlrev_b32_e32 v28, 16, v117
	v_and_b32_e32 v29, 0xffff0000, v117
	v_pk_mul_f32 v[28:29], v[34:35], v[28:29] op_sel_hi:[0,1]
	v_pk_fma_f32 v[26:27], v[26:27], v[28:29], v[30:31]
	v_lshl_add_u64 v[28:29], v[36:37], 2, s[88:89]
	v_lshl_add_u64 v[32:33], v[36:37], 1, s[6:7]
	v_lshl_add_u64 v[28:29], v[28:29], 0, v[178:179]
	s_and_b64 vcc, exec, s[36:37]
	global_store_dwordx4 v[28:29], v[24:27], off nt
	s_cbranch_vccnz .LBB0_624
	v_lshlrev_b32_e32 v178, 1, v148
	v_cvt_pk_bf16_f32 v30, v24, v25
	v_cvt_pk_bf16_f32 v31, v26, v27
	v_lshl_add_u64 v[36:37], v[32:33], 0, v[178:179]
	global_store_dwordx2 v[36:37], v[30:31], off
.LBB0_624:
	v_mov_b32_e32 v35, v34
	v_lshlrev_b32_e32 v30, 16, v112
	v_and_b32_e32 v31, 0xffff0000, v112
	v_pk_mul_f32 v[30:31], v[34:35], v[30:31]
	s_and_b64 vcc, exec, s[36:37]
	v_pk_fma_f32 v[16:17], v[20:21], v[30:31], v[16:17]
	v_lshlrev_b32_e32 v20, 16, v113
	v_and_b32_e32 v21, 0xffff0000, v113
	v_pk_mul_f32 v[20:21], v[34:35], v[20:21]
	s_nop 0
	v_pk_fma_f32 v[18:19], v[22:23], v[20:21], v[18:19]
	global_store_dwordx4 v[28:29], v[16:19], off offset:1024 nt
	s_cbranch_vccnz .LBB0_626
	v_lshlrev_b32_e32 v178, 1, v148
	v_cvt_pk_bf16_f32 v20, v16, v17
	v_cvt_pk_bf16_f32 v21, v18, v19
	v_lshl_add_u64 v[22:23], v[32:33], 0, v[178:179]
	global_store_dwordx2 v[22:23], v[20:21], off offset:512
.LBB0_626:
	v_lshlrev_b32_e32 v20, 16, v110
	v_and_b32_e32 v21, 0xffff0000, v110
	v_pk_mul_f32 v[20:21], v[34:35], v[20:21]
	s_and_b64 vcc, exec, s[36:37]
	v_pk_fma_f32 v[8:9], v[20:21], v[12:13], v[8:9]
	v_lshlrev_b32_e32 v12, 16, v111
	v_and_b32_e32 v13, 0xffff0000, v111
	v_pk_mul_f32 v[12:13], v[34:35], v[12:13]
	s_nop 0
	v_pk_fma_f32 v[10:11], v[12:13], v[14:15], v[10:11]
	global_store_dwordx4 v[28:29], v[8:11], off offset:2048 nt
	s_cbranch_vccnz .LBB0_628
	v_lshlrev_b32_e32 v178, 1, v148
	v_cvt_pk_bf16_f32 v12, v8, v9
	v_cvt_pk_bf16_f32 v13, v10, v11
	v_lshl_add_u64 v[14:15], v[32:33], 0, v[178:179]
	global_store_dwordx2 v[14:15], v[12:13], off offset:1024
.LBB0_628:
	v_lshlrev_b32_e32 v12, 16, v108
	v_and_b32_e32 v13, 0xffff0000, v108
	v_pk_mul_f32 v[12:13], v[34:35], v[12:13]
	s_and_b64 vcc, exec, s[36:37]
	v_pk_fma_f32 v[0:1], v[12:13], v[4:5], v[0:1]
	v_lshlrev_b32_e32 v4, 16, v109
	v_and_b32_e32 v5, 0xffff0000, v109
	v_pk_mul_f32 v[4:5], v[34:35], v[4:5]
	s_nop 0
	v_pk_fma_f32 v[2:3], v[4:5], v[6:7], v[2:3]
	global_store_dwordx4 v[28:29], v[0:3], off offset:3072 nt
	s_cbranch_vccnz .LBB0_630
	v_lshlrev_b32_e32 v178, 1, v148
	v_cvt_pk_bf16_f32 v4, v0, v1
	v_cvt_pk_bf16_f32 v5, v2, v3
	v_lshl_add_u64 v[6:7], v[32:33], 0, v[178:179]
	global_store_dwordx2 v[6:7], v[4:5], off offset:1536
